# indexer relu-weighted head sum with packed f32 mul/fma
# baseline (speedup 1.0000x reference)
; #define TILE_LOAD(SLOT, CC, TT) do { const bf16_t* kp = P.KI + (rowb + 64 * (CC) + 16 * (TT) + r16) * 64 + 8 * g; Bk[SLOT][0] = *(const bf16x8*)kp; Bk[SLOT][1] = *(const bf16x8*)(kp + 32); } while (0)
; #define TILE_MATH(SLOT, TT) do { _Pragma("unroll") for (int q = 0; q < 4; ++q) { f32x4 a = {0.f, 0.f, 0.f, 0.f}; \
;             a = mfma16(Aq[q][0], Bk[SLOT][0], a); a = mfma16(Aq[q][1], Bk[SLOT][1], a); \
;             pv[q][TT] = wq[q][0] * fmaxf(a[0], 0.f) + wq[q][1] * fmaxf(a[1], 0.f) + wq[q][2] * fmaxf(a[2], 0.f) + wq[q][3] * fmaxf(a[3], 0.f); } } while (0)
; __device__ __forceinline__ void attn_item(const Ptrs& P, unsigned char* lds, int b, int tq0, int tid) {
;     ...
;         if (ni > 0) { TILE_LOAD(0, w, 0); TILE_LOAD(1, w, 1); }
; #pragma unroll 1
;         for (int it = 0; it < ni; ++it) {
;             const int c = 8 * it + w; const bool more = it + 1 < ni;
;             float pv[4][4], sv[4];
;             TILE_LOAD(2, c, 2); TILE_MATH(0, 0);
;             TILE_LOAD(3, c, 3); TILE_MATH(1, 1);
;             if (more) TILE_LOAD(0, c + 8, 0);
;             TILE_MATH(2, 2);
;             if (more) TILE_LOAD(1, c + 8, 1);
;             TILE_MATH(3, 3);
.Lidx_loop:
	s_waitcnt vmcnt(6)
	v_mfma_f32_16x16x32_bf16 v[80:83], v[0:3], v[48:51], 0
	v_mfma_f32_16x16x32_bf16 v[84:87], v[8:11], v[48:51], 0
	v_mfma_f32_16x16x32_bf16 v[88:91], v[16:19], v[48:51], 0
	v_mfma_f32_16x16x32_bf16 v[92:95], v[24:27], v[48:51], 0
	v_mfma_f32_16x16x32_bf16 v[80:83], v[4:7], v[52:55], v[80:83]
	v_mfma_f32_16x16x32_bf16 v[84:87], v[12:15], v[52:55], v[84:87]
	v_mfma_f32_16x16x32_bf16 v[88:91], v[20:23], v[52:55], v[88:91]
	v_mfma_f32_16x16x32_bf16 v[92:95], v[28:31], v[52:55], v[92:95]
	global_load_dwordx4 v[48:51], v[150:151], off
	global_load_dwordx4 v[52:55], v[150:151], off offset:1024
	s_waitcnt vmcnt(6)
	v_mfma_f32_16x16x32_bf16 v[96:99], v[0:3], v[56:59], 0
	v_mfma_f32_16x16x32_bf16 v[100:103], v[8:11], v[56:59], 0
	v_mfma_f32_16x16x32_bf16 v[104:107], v[16:19], v[56:59], 0
	v_mfma_f32_16x16x32_bf16 v[108:111], v[24:27], v[56:59], 0
	v_mfma_f32_16x16x32_bf16 v[96:99], v[4:7], v[60:63], v[96:99]
	v_mfma_f32_16x16x32_bf16 v[100:103], v[12:15], v[60:63], v[100:103]
	v_mfma_f32_16x16x32_bf16 v[104:107], v[20:23], v[60:63], v[104:107]
	v_mfma_f32_16x16x32_bf16 v[108:111], v[28:31], v[60:63], v[108:111]
	global_load_dwordx4 v[56:59], v[150:151], off offset:2048
	global_load_dwordx4 v[60:63], v[150:151], off offset:3072
	v_max_f32_e32 v80, 0, v80
	v_max_f32_e32 v84, 0, v84
	v_max_f32_e32 v88, 0, v88
	v_max_f32_e32 v92, 0, v92
	v_max_f32_e32 v81, 0, v81
	v_max_f32_e32 v85, 0, v85
	v_max_f32_e32 v89, 0, v89
	v_max_f32_e32 v93, 0, v93
	v_max_f32_e32 v82, 0, v82
	v_max_f32_e32 v86, 0, v86
	v_max_f32_e32 v90, 0, v90
	v_max_f32_e32 v94, 0, v94
	v_max_f32_e32 v83, 0, v83
	v_max_f32_e32 v87, 0, v87
	v_max_f32_e32 v91, 0, v91
	v_max_f32_e32 v95, 0, v95
	v_pk_mul_f32 v[158:159], v[44:45], v[80:81]
	v_pk_mul_f32 v[160:161], v[40:41], v[84:85]
	v_pk_mul_f32 v[162:163], v[36:37], v[88:89]
	v_pk_mul_f32 v[148:149], v[32:33], v[92:93]
	v_pk_fma_f32 v[158:159], v[46:47], v[82:83], v[158:159]
	v_pk_fma_f32 v[160:161], v[42:43], v[86:87], v[160:161]
	v_pk_fma_f32 v[162:163], v[38:39], v[90:91], v[162:163]
	v_pk_fma_f32 v[148:149], v[34:35], v[94:95], v[148:149]
	v_add_f32_e32 v132, v158, v159
	v_add_f32_e32 v136, v160, v161
	v_add_f32_e32 v140, v162, v163
	v_add_f32_e32 v144, v148, v149
	s_waitcnt vmcnt(6)
	v_mfma_f32_16x16x32_bf16 v[80:83], v[0:3], v[64:67], 0
	v_mfma_f32_16x16x32_bf16 v[84:87], v[8:11], v[64:67], 0
	v_mfma_f32_16x16x32_bf16 v[88:91], v[16:19], v[64:67], 0
	v_mfma_f32_16x16x32_bf16 v[92:95], v[24:27], v[64:67], 0
	v_mfma_f32_16x16x32_bf16 v[80:83], v[4:7], v[68:71], v[80:83]
	v_mfma_f32_16x16x32_bf16 v[84:87], v[12:15], v[68:71], v[84:87]
	v_mfma_f32_16x16x32_bf16 v[88:91], v[20:23], v[68:71], v[88:91]
	v_mfma_f32_16x16x32_bf16 v[92:95], v[28:31], v[68:71], v[92:95]
	global_load_dwordx4 v[64:67], v[152:153], off
	global_load_dwordx4 v[68:71], v[152:153], off offset:1024
	v_max_f32_e32 v96, 0, v96
	v_max_f32_e32 v100, 0, v100
	v_max_f32_e32 v104, 0, v104
	v_max_f32_e32 v108, 0, v108
	v_max_f32_e32 v97, 0, v97
	v_max_f32_e32 v101, 0, v101
	v_max_f32_e32 v105, 0, v105
	v_max_f32_e32 v109, 0, v109
	v_max_f32_e32 v98, 0, v98
	v_max_f32_e32 v102, 0, v102
	v_max_f32_e32 v106, 0, v106
	v_max_f32_e32 v110, 0, v110
	v_max_f32_e32 v99, 0, v99
	v_max_f32_e32 v103, 0, v103
	v_max_f32_e32 v107, 0, v107
	v_max_f32_e32 v111, 0, v111
	v_pk_mul_f32 v[158:159], v[44:45], v[96:97]
	v_pk_mul_f32 v[160:161], v[40:41], v[100:101]
	v_pk_mul_f32 v[162:163], v[36:37], v[104:105]
	v_pk_mul_f32 v[148:149], v[32:33], v[108:109]
	v_pk_fma_f32 v[158:159], v[46:47], v[98:99], v[158:159]
	v_pk_fma_f32 v[160:161], v[42:43], v[102:103], v[160:161]
	v_pk_fma_f32 v[162:163], v[38:39], v[106:107], v[162:163]
	v_pk_fma_f32 v[148:149], v[34:35], v[110:111], v[148:149]
	v_add_f32_e32 v133, v158, v159
	v_add_f32_e32 v137, v160, v161
	v_add_f32_e32 v141, v162, v163
	v_add_f32_e32 v145, v148, v149
	s_waitcnt vmcnt(6)
; __device__ __forceinline__ unsigned f2key(float f) { const unsigned u = __builtin_bit_cast(unsigned, f); return (u & 0x80000000u) ? ~u : (u | 0x80000000u); }
; #define TILE_LOAD(SLOT, CC, TT) do { const bf16_t* kp = P.KI + (rowb + 64 * (CC) + 16 * (TT) + r16) * 64 + 8 * g; Bk[SLOT][0] = *(const bf16x8*)kp; Bk[SLOT][1] = *(const bf16x8*)(kp + 32); } while (0)
; #define TILE_MATH(SLOT, TT) do { _Pragma("unroll") for (int q = 0; q < 4; ++q) { f32x4 a = {0.f, 0.f, 0.f, 0.f}; \
;             a = mfma16(Aq[q][0], Bk[SLOT][0], a); a = mfma16(Aq[q][1], Bk[SLOT][1], a); \
;             pv[q][TT] = wq[q][0] * fmaxf(a[0], 0.f) + wq[q][1] * fmaxf(a[1], 0.f) + wq[q][2] * fmaxf(a[2], 0.f) + wq[q][3] * fmaxf(a[3], 0.f); } } while (0)
; __device__ __forceinline__ void attn_item(const Ptrs& P, unsigned char* lds, int b, int tq0, int tid) {
;     ...
;             TILE_LOAD(2, c, 2); TILE_MATH(0, 0);
;             TILE_LOAD(3, c, 3); TILE_MATH(1, 1);
;             if (more) TILE_LOAD(0, c + 8, 0);
;             TILE_MATH(2, 2);
;             if (more) TILE_LOAD(1, c + 8, 1);
;             TILE_MATH(3, 3);
; #pragma unroll
;             for (int q = 0; q < 4; ++q) { float a0 = pv[q][0], b0 = pv[q][2], a1 = pv[q][1], b1 = pv[q][3];
;                 asm("s_nop 1\n\tv_permlane32_swap_b32 %0, %1" : "+v"(a0), "+v"(b0));
;                 asm("s_nop 1\n\tv_permlane32_swap_b32 %0, %1" : "+v"(a1), "+v"(b1));
;                 float x = a0 + b0, y = a1 + b1;
;                 asm("s_nop 1\n\tv_permlane16_swap_b32 %0, %1" : "+v"(x), "+v"(y));
;                 sv[q] = x + y; }
;             const int s = 64 * c + lane;
; #pragma unroll
;             for (int q = 0; q < 4; ++q) KB[q * 8192 + s] = (s <= tq0 + q) ? f2key(sv[q]) : 0u;
	v_mfma_f32_16x16x32_bf16 v[96:99], v[0:3], v[72:75], 0
	v_mfma_f32_16x16x32_bf16 v[100:103], v[8:11], v[72:75], 0
	v_mfma_f32_16x16x32_bf16 v[104:107], v[16:19], v[72:75], 0
	v_mfma_f32_16x16x32_bf16 v[108:111], v[24:27], v[72:75], 0
	v_mfma_f32_16x16x32_bf16 v[96:99], v[4:7], v[76:79], v[96:99]
	v_mfma_f32_16x16x32_bf16 v[100:103], v[12:15], v[76:79], v[100:103]
	v_mfma_f32_16x16x32_bf16 v[104:107], v[20:23], v[76:79], v[104:107]
	v_mfma_f32_16x16x32_bf16 v[108:111], v[28:31], v[76:79], v[108:111]
	global_load_dwordx4 v[72:75], v[152:153], off offset:2048
	global_load_dwordx4 v[76:79], v[152:153], off offset:3072
	v_lshl_add_u64 v[150:151], v[150:151], 0, s[18:19]
	v_lshl_add_u64 v[152:153], v[152:153], 0, s[18:19]
	v_max_f32_e32 v80, 0, v80
	v_max_f32_e32 v84, 0, v84
	v_max_f32_e32 v88, 0, v88
	v_max_f32_e32 v92, 0, v92
	v_max_f32_e32 v81, 0, v81
	v_max_f32_e32 v85, 0, v85
	v_max_f32_e32 v89, 0, v89
	v_max_f32_e32 v93, 0, v93
	v_max_f32_e32 v82, 0, v82
	v_max_f32_e32 v86, 0, v86
	v_max_f32_e32 v90, 0, v90
	v_max_f32_e32 v94, 0, v94
	v_max_f32_e32 v83, 0, v83
	v_max_f32_e32 v87, 0, v87
	v_max_f32_e32 v91, 0, v91
	v_max_f32_e32 v95, 0, v95
	v_pk_mul_f32 v[158:159], v[44:45], v[80:81]
	v_pk_mul_f32 v[160:161], v[40:41], v[84:85]
	v_pk_mul_f32 v[162:163], v[36:37], v[88:89]
	v_pk_mul_f32 v[148:149], v[32:33], v[92:93]
	v_pk_fma_f32 v[158:159], v[46:47], v[82:83], v[158:159]
	v_pk_fma_f32 v[160:161], v[42:43], v[86:87], v[160:161]
	v_pk_fma_f32 v[162:163], v[38:39], v[90:91], v[162:163]
	v_pk_fma_f32 v[148:149], v[34:35], v[94:95], v[148:149]
	v_add_f32_e32 v134, v158, v159
	v_add_f32_e32 v138, v160, v161
	v_add_f32_e32 v142, v162, v163
	v_add_f32_e32 v146, v148, v149
	v_max_f32_e32 v96, 0, v96
	v_max_f32_e32 v100, 0, v100
	v_max_f32_e32 v104, 0, v104
	v_max_f32_e32 v108, 0, v108
	v_max_f32_e32 v97, 0, v97
	v_max_f32_e32 v101, 0, v101
	v_max_f32_e32 v105, 0, v105
	v_max_f32_e32 v109, 0, v109
	v_max_f32_e32 v98, 0, v98
	v_max_f32_e32 v102, 0, v102
	v_max_f32_e32 v106, 0, v106
	v_max_f32_e32 v110, 0, v110
	v_max_f32_e32 v99, 0, v99
	v_max_f32_e32 v103, 0, v103
	v_max_f32_e32 v107, 0, v107
	v_max_f32_e32 v111, 0, v111
	v_pk_mul_f32 v[158:159], v[44:45], v[96:97]
	v_pk_mul_f32 v[160:161], v[40:41], v[100:101]
	v_pk_mul_f32 v[162:163], v[36:37], v[104:105]
	v_pk_mul_f32 v[148:149], v[32:33], v[108:109]
	v_pk_fma_f32 v[158:159], v[46:47], v[98:99], v[158:159]
	v_pk_fma_f32 v[160:161], v[42:43], v[102:103], v[160:161]
	v_pk_fma_f32 v[162:163], v[38:39], v[106:107], v[162:163]
	v_pk_fma_f32 v[148:149], v[34:35], v[110:111], v[148:149]
	v_add_f32_e32 v135, v158, v159
	v_add_f32_e32 v139, v160, v161
	v_add_f32_e32 v143, v162, v163
	v_add_f32_e32 v147, v148, v149
	s_nop 1
	v_permlane32_swap_b32_e32 v132, v134
	v_permlane32_swap_b32_e32 v133, v135
	v_permlane32_swap_b32_e32 v136, v138
	v_permlane32_swap_b32_e32 v137, v139
	v_permlane32_swap_b32_e32 v140, v142
	v_permlane32_swap_b32_e32 v141, v143
	v_permlane32_swap_b32_e32 v144, v146
	v_permlane32_swap_b32_e32 v145, v147
	v_add_f32_e32 v112, v132, v134
	v_add_f32_e32 v113, v133, v135
	v_add_f32_e32 v114, v136, v138
	v_add_f32_e32 v115, v137, v139
	v_add_f32_e32 v116, v140, v142
	v_add_f32_e32 v117, v141, v143
	v_add_f32_e32 v118, v144, v146
	v_add_f32_e32 v119, v145, v147
	s_nop 1
	v_permlane16_swap_b32_e32 v112, v113
	v_permlane16_swap_b32_e32 v114, v115
	v_permlane16_swap_b32_e32 v116, v117
	v_permlane16_swap_b32_e32 v118, v119
	v_add_u32_e32 v156, 0x800, v130
	v_add_u32_e32 v157, 0x800, v155
	v_add_f32_e32 v120, v112, v113
	v_add_f32_e32 v121, v114, v115
	v_add_f32_e32 v122, v116, v117
	v_add_f32_e32 v123, v118, v119
	v_ashrrev_i32_e32 v112, 31, v120
	v_ashrrev_i32_e32 v113, 31, v121
	v_ashrrev_i32_e32 v114, 31, v122
	v_ashrrev_i32_e32 v115, 31, v123
	v_cmp_le_u32_e32 vcc, v154, v124
	v_cmp_le_u32_e64 s[16:17], v154, v128
	v_cmp_le_u32_e64 s[44:45], v154, v129
	v_cmp_le_u32_e64 s[78:79], v154, v126
	v_or_b32_e32 v112, 0x80000000, v112
	v_or_b32_e32 v113, 0x80000000, v113
	v_or_b32_e32 v114, 0x80000000, v114
	v_or_b32_e32 v115, 0x80000000, v115
	v_xor_b32_e32 v120, v120, v112
	v_xor_b32_e32 v121, v121, v113
	v_xor_b32_e32 v122, v122, v114
	v_xor_b32_e32 v123, v123, v115
	v_cndmask_b32_e32 v120, 0, v120, vcc
	v_cndmask_b32_e64 v121, 0, v121, s[16:17]
	v_cndmask_b32_e64 v122, 0, v122, s[44:45]
	v_cndmask_b32_e64 v123, 0, v123, s[78:79]
	ds_write2st64_b32 v130, v120, v121 offset1:128
	ds_write2st64_b32 v155, v122, v123 offset1:128
	v_mov_b32_e32 v130, v156
	v_mov_b32_e32 v155, v157
	v_add_u32_e32 v154, 0x200, v154
	s_add_i32 s20, s20, 1
	s_cmp_lt_u32 s20, s14
	s_cbranch_scc1 .Lidx_loop
	s_waitcnt vmcnt(0)
	s_branch .LBB0_479
	s_nop 0
	s_nop 0
	s_nop 0
	s_nop 0
	s_nop 0
	s_nop 0
	s_nop 0
